# next-layer weight conversion split: first 3072 items converted at the end of P8 by the 192 workgroups without a fifth up-GEMM tile, rest in P5 (4 whole rounds + leftovers on cq-GEMM workgroups)
# speedup vs baseline: 1.0025x; 1.0025x over previous
_Z8fwd_mega4Args:
	s_load_dword s58, s[0:1], 0xd8
	s_mov_b32 s100, 0
	s_load_dwordx4 s[40:43], s[0:1], 0xc0
	s_load_dwordx2 s[34:35], s[0:1], 0xd0
	s_add_u32 s8, s0, 0xd0
	v_and_b32_e32 v193, 0x3ff, v0
	s_addc_u32 s9, s1, 0
	v_readfirstlane_b32 s3, v193
	v_cmp_gt_u32_e32 vcc, 64, v193
	s_and_saveexec_b64 s[4:5], vcc
	v_lshl_add_u32 v1, v193, 2, 0
	v_add_u32_e32 v1, 0x20000, v1
	v_mov_b32_e32 v2, 0
	ds_write_b32 v1, v2
	s_or_b64 exec, exec, s[4:5]
	s_load_dwordx16 s[12:27], s[0:1], 0x40
	s_waitcnt lgkmcnt(0)
	s_add_u32 s60, s42, 0x1000
	s_barrier
	v_writelane_b32 v253, s12, 0
	s_addc_u32 s61, s43, 0
	s_getreg_b32 s10, hwreg(HW_REG_XCC_ID, 0, 4)
	v_writelane_b32 v253, s13, 1
	v_writelane_b32 v253, s14, 2
	v_writelane_b32 v253, s15, 3
	v_writelane_b32 v253, s16, 4
	v_writelane_b32 v253, s17, 5
	v_writelane_b32 v253, s18, 6
	v_writelane_b32 v253, s19, 7
	v_writelane_b32 v253, s20, 8
	v_writelane_b32 v253, s21, 9
	v_writelane_b32 v253, s22, 10
	v_writelane_b32 v253, s23, 11
	v_writelane_b32 v253, s24, 12
	v_writelane_b32 v253, s25, 13
	v_writelane_b32 v253, s26, 14
	v_writelane_b32 v253, s27, 15
	s_load_dwordx16 s[12:27], s[0:1], 0x80
	v_cmp_eq_u32_e64 s[6:7], 0, v193
	s_waitcnt lgkmcnt(0)
	v_writelane_b32 v253, s12, 16
	s_nop 1
	v_writelane_b32 v253, s13, 17
	v_writelane_b32 v253, s14, 18
	v_writelane_b32 v253, s15, 19
	v_writelane_b32 v253, s16, 20
	v_writelane_b32 v253, s17, 21
	v_writelane_b32 v253, s18, 22
	v_writelane_b32 v253, s19, 23
	v_writelane_b32 v253, s20, 24
	v_writelane_b32 v253, s21, 25
	v_writelane_b32 v253, s22, 26
	v_writelane_b32 v253, s23, 27
	v_writelane_b32 v253, s24, 28
	v_writelane_b32 v253, s25, 29
	v_writelane_b32 v253, s26, 30
	v_writelane_b32 v253, s27, 31
	s_mov_b64 s[4:5], exec
	v_writelane_b32 v253, s6, 32
	s_nop 1
	v_writelane_b32 v253, s7, 33
	s_and_b64 s[6:7], s[4:5], s[6:7]
	s_mov_b64 exec, s[6:7]
	s_cbranch_execz .LBB0_5
	s_mov_b64 s[6:7], exec
	v_mbcnt_lo_u32_b32 v1, s6, 0
	v_mbcnt_hi_u32_b32 v1, s7, v1
	v_cmp_eq_u32_e32 vcc, 0, v1
	s_and_b64 s[12:13], exec, vcc
	s_mov_b64 exec, s[12:13]
	s_cbranch_execz .LBB0_5
	s_lshl_b32 s10, s10, 8
	s_and_b32 s10, s10, 0xf00
	s_bcnt1_i32_b64 s6, s[6:7]
	v_mov_b32_e32 v1, s10
	v_mov_b32_e32 v2, s6
	global_atomic_add v1, v2, s[60:61] offset:1024

.LBB0_790:
	s_cmpk_lg_i32 s34, 0x100
	s_cbranch_scc1 .Lcv5_orig
	v_readlane_b32 s0, v255, 43
	s_cmp_eq_u32 s0, 3
	s_cbranch_scc1 .LBB0_881
	v_readlane_b32 s0, v254, 34
	s_movk_i32 s1, 0x5e0
	s_movk_i32 s101, 9088
	s_cmp_lt_i32 s0, 0
	s_cbranch_scc1 .Lcv5_gemm
	s_addk_i32 s0, 3072
	s_branch .Lcv5_go
.Lcv5_gemm:
	s_addk_i32 s0, 0x220
	s_cmpk_ge_i32 s0, 128
	s_cbranch_scc1 .LBB0_881
	s_addk_i32 s0, 9088
	s_movk_i32 s1, 0x220
	s_movk_i32 s101, 0x2400
.Lcv5_go:
	v_writelane_b32 v255, s1, 57
	s_nop 1
	v_writelane_b32 v255, s0, 58
	s_nop 1
	s_branch .Lcv_entry
.Lcv5_orig:
	v_readlane_b32 s0, v254, 33
	s_nop 1
	v_writelane_b32 v255, s0, 57
	v_readlane_b32 s0, v254, 34
	s_nop 1
	v_writelane_b32 v255, s0, 58
	s_movk_i32 s101, 0x2400
	s_nop 1
	v_readlane_b32 s0, v255, 43
	v_readlane_b32 s4, v254, 30
	v_readlane_b32 s1, v255, 44
	s_cmp_lg_u32 s0, 3
	v_readlane_b32 s5, v254, 31
	s_cselect_b64 s[0:1], -1, 0
	s_xor_b64 s[4:5], s[4:5], -1
	s_and_b64 s[0:1], s[4:5], s[0:1]
	s_and_b64 vcc, exec, s[0:1]
	s_cbranch_vccz .LBB0_881
	v_readlane_b32 s0, v254, 35
	v_readlane_b32 s1, v254, 36
	s_andn2_b64 vcc, exec, s[0:1]
	s_cbranch_vccnz .LBB0_881
.Lcv_entry:
	v_readlane_b32 s0, v255, 43
	v_readlane_b32 s1, v255, 44
	s_add_i32 s92, s0, 1
	s_mul_i32 s1, s92, 0x2500000
	v_readlane_b32 s3, v253, 59
	s_mul_hi_u32 s0, s92, 0x2500000
	s_add_u32 s6, s3, s1
	v_readlane_b32 s1, v253, 58
	s_addc_u32 s7, s1, s0
	s_lshl_b64 s[0:1], s[92:93], 24
	s_add_u32 s65, s6, 0x1d00000
	s_addc_u32 s67, s7, 0
	s_lshl_b32 s4, s92, 10
	s_add_u32 s72, s6, 0x1500000
	s_addc_u32 s73, s7, 0
	s_lshl_b64 s[8:9], s[92:93], 20
	s_add_u32 s82, s6, 0x1480000
	s_addc_u32 s3, s7, 0
	v_writelane_b32 v255, s3, 48
	s_add_u32 s3, s6, 0x1300000
	v_writelane_b32 v255, s3, 49
	s_addc_u32 s3, s7, 0
	s_lshl_b64 s[10:11], s[92:93], 22
	s_add_u32 s30, s6, 0x1100000
	s_addc_u32 s31, s7, 0
	s_add_u32 s16, s6, 0xf00000
	s_addc_u32 s20, s7, 0
	s_add_u32 s35, s6, 0xd00000
	v_readlane_b32 s48, v253, 16
	s_addc_u32 s26, s7, 0
	v_readlane_b32 s60, v253, 28
	v_writelane_b32 v255, s3, 50
	v_readlane_b32 s61, v253, 29
	s_add_u32 s15, s60, s0
	v_readlane_b32 s58, v253, 26
	v_writelane_b32 v255, s15, 51
	s_addc_u32 s15, s61, s1
	v_readlane_b32 s59, v253, 27
	v_writelane_b32 v255, s15, 52
	s_add_u32 s0, s58, s0
	s_mov_b32 s5, s93
	v_writelane_b32 v255, s0, 53
	s_addc_u32 s0, s59, s1
	v_readlane_b32 s56, v253, 24
	v_writelane_b32 v255, s0, 54
	s_lshl_b64 s[0:1], s[4:5], 2
	v_readlane_b32 s57, v253, 25
	s_add_u32 s4, s56, s0
	v_readlane_b32 s54, v253, 22
	s_addc_u32 s5, s57, s1
	v_readlane_b32 s55, v253, 23
	s_add_u32 s15, s54, s8
	v_readlane_b32 s50, v253, 18
	v_writelane_b32 v255, s15, 55
	s_addc_u32 s15, s55, s9
	v_readlane_b32 s49, v253, 17
	v_readlane_b32 s51, v253, 19
	v_readlane_b32 s52, v253, 20
	v_readlane_b32 s53, v253, 21
	v_readlane_b32 s62, v253, 30
	v_readlane_b32 s63, v253, 31
	s_add_u32 s88, s50, s8
	s_addc_u32 s89, s51, s9
	v_readlane_b32 s48, v253, 0
	v_readlane_b32 s62, v253, 14
	v_readlane_b32 s63, v253, 15
	s_add_u32 s8, s62, s0
	v_readlane_b32 s60, v253, 12
	s_addc_u32 s9, s63, s1
	s_mul_hi_u32 s3, s92, 0x1a00000
	s_mul_i32 s14, s92, 0x1a00000
	v_readlane_b32 s61, v253, 13
	s_add_u32 s92, s60, s10
	v_readlane_b32 s58, v253, 10
	s_addc_u32 s96, s61, s11
	v_readlane_b32 s59, v253, 11
	s_add_u32 s97, s58, s10
	v_readlane_b32 s56, v253, 8
	s_addc_u32 s18, s59, s11
	v_readlane_b32 s57, v253, 9
	s_add_u32 s19, s56, s10
	v_readlane_b32 s50, v253, 2
	s_addc_u32 s22, s57, s11
	v_readlane_b32 s51, v253, 3
	v_readlane_b32 s54, v253, 6
	s_add_u32 s23, s50, s14
	s_addc_u32 s54, s51, s3
	v_readlane_b32 s49, v253, 1
	s_add_u32 s10, s48, s0
	v_readlane_b32 s29, v255, 58
	s_addc_u32 s11, s49, s1
	s_lshl_b32 s0, s29, 6
	v_readlane_b32 s52, v253, 4
	v_readlane_b32 s55, v253, 7
	v_readlane_b32 s48, v255, 57
	s_add_i32 s69, s0, 0x7fffe400
	s_lshl_b32 s0, s29, 1
	v_readlane_b32 s50, v254, 41
	v_writelane_b32 v255, s15, 56
	s_lshl_b32 s55, s29, 5
	s_lshl_b32 s68, s48, 5
	s_lshl_b32 s24, s48, 6
	s_add_i32 s25, s0, 0x1c800
	s_lshl_b32 s86, s48, 1
	s_lshl_b32 s87, s29, 3
	s_lshl_b32 s28, s48, 3
	v_and_b32_e32 v12, 63, v193
	v_readlane_b32 s33, v253, 35
	v_readlane_b32 s51, v254, 42
	s_movk_i32 s49, 0x84
	s_movk_i32 s52, 0x6800
	v_readlane_b32 s53, v253, 5
	s_branch .LBB0_795

.LBB0_794:
	s_add_i32 s29, s29, s48
	s_add_i32 s55, s55, s68
	s_add_i32 s69, s69, s24
	s_add_i32 s25, s25, s86
	s_add_i32 s87, s87, s28
	s_cmp_lt_i32 s29, s101
	s_cbranch_scc0 .LBB0_880

.LBB0_880:
	v_readlane_b32 s52, v255, 40
	v_readlane_b32 s53, v255, 41
	v_readlane_b32 s96, v254, 29
	v_readlane_b32 s20, v255, 39
	v_readlane_b32 s26, v255, 21
	s_mov_b64 s[42:43], 0x60
	v_readlane_b32 s33, v255, 42
	s_cmp_eq_u32 s100, 8
	s_cbranch_scc1 .Lcv_ret8

.LBB0_1157:
	s_cmpk_lg_i32 s34, 0x100
	s_cbranch_scc1 .Lcv_skip8
	v_readlane_b32 s0, v255, 43
	s_cmp_eq_u32 s0, 3
	s_cbranch_scc1 .Lcv_skip8
	s_cmpk_lt_u32 s2, 64
	s_cbranch_scc1 .Lcv_skip8
	v_readlane_b32 s0, v254, 34
	s_movk_i32 s1, 0x600
	s_movk_i32 s101, 3072
	s_addk_i32 s0, 32
	v_writelane_b32 v255, s1, 57
	s_nop 1
	v_writelane_b32 v255, s0, 58
	s_nop 1
	s_mov_b32 s100, 8
	s_branch .Lcv_entry
.Lcv_ret8:
	s_mov_b32 s100, 0
